# same as previous but with the original K/V staging loop (A/B of the staging rewrite)
# speedup vs baseline: 1.0193x; 1.0106x over previous
; __device__ __forceinline__ void attn_item(const Args& a, LAS unsigned char* lds, int item, int wave, int lane) {
;     ...
;     __syncthreads();
;     const int r = wave >> 1, qh = wave & 1, hq = kvh * 4 + r, ql = lane & 31, hi = lane >> 5;
;     const float sink = a.in[6][hq];
;     const float* qnw = a.in[4];
;     const float L2E = 1.4426950408889634f;
;     for (int q4 = 0; q4 < 4; ++q4) {
;         const int bl = q4 >> 1, qb = q4 & 1, blk = blk0 + bl;
;         const int qblk = 2 * qh + qb;
;         const size_t qrow = (size_t)b * SEQ + blk * 128 + qblk * 32 + ql;
;         bf16x8 qf[4];
;         {
;             u32x4 qw[4]; float ss = 0.f;
; #pragma unroll
;             for (int ks = 0; ks < 4; ++ks) { qw[ks] = *(const u32x4*)(QB + qrow * DM + hq * 64 + 16 * ks + 8 * hi);
.LBB0_254:
	s_or_b64 exec, exec, s[70:71]
	s_lshl_b32 s42, s67, 2
	s_add_i32 s62, s42, s41
	s_lshl_b32 s42, s62, 2
	v_mov_b32_e32 v0, s42
	s_waitcnt lgkmcnt(0)
	s_barrier
	global_load_dword v98, v0, s[88:89]
	s_ashr_i32 s67, s66, 31
	s_lshl_b32 s62, s62, 7
	s_lshl_b64 s[42:43], s[66:67], 13
	v_lshl_add_u64 v[116:117], v[108:109], 0, s[62:63]
	v_lshl_add_u64 v[118:119], v[114:115], 0, s[62:63]
	s_lshl_b32 s100, s33, 12
	s_add_i32 s100, s100, 113664
	v_lshl_add_u32 v238, v128, 4, s100
	s_lshl_b32 s98, s85, 7
	s_add_i32 s98, s98, s42
	s_lshl_b32 s99, s65, 5
	s_or_b32 s98, s98, s99
	v_or_b32_e32 v222, s98, v130
	v_lshlrev_b32_e32 v222, 11, v222
	v_mov_b32_e32 v223, 0
	v_lshl_add_u64 v[220:221], v[116:117], 0, v[222:223]
	s_add_i32 m0, s100, 0
	s_nop 0
	global_load_lds_dwordx4 v[220:221], off
	s_add_i32 m0, s100, 992
	s_nop 0
	global_load_lds_dwordx4 v[220:221], off offset:32
	s_add_i32 m0, s100, 1984
	s_nop 0
	global_load_lds_dwordx4 v[220:221], off offset:64
	s_add_i32 m0, s100, 2976
	s_nop 0
	global_load_lds_dwordx4 v[220:221], off offset:96
	s_mov_b32 s62, 0
	s_waitcnt vmcnt(0)
	v_mul_f32_e32 v138, 0x3fb8aa3b, v98
	s_branch .LBB0_256

; __device__ __forceinline__ unsigned cvt_pk(float lo, float hi) { unsigned r; asm volatile("v_cvt_pk_bf16_f32 %0, %1, %2" : "=v"(r) : "v"(lo), "v"(hi)); return r; }
; __device__ __forceinline__ float bf_lo(unsigned w) { return __uint_as_float(w << 16); }
; __device__ __forceinline__ float bf_hi(unsigned w) { return __uint_as_float(w & 0xffff0000u); }
; __device__ __forceinline__ void attn_item(const Args& a, LAS unsigned char* lds, int item, int wave, int lane) {
;     ...
;     for (int q4 = 0; q4 < 4; ++q4) {
;         const int bl = q4 >> 1, qb = q4 & 1, blk = blk0 + bl;
;         const int qblk = 2 * qh + qb;
;         const size_t qrow = (size_t)b * SEQ + blk * 128 + qblk * 32 + ql;
;         bf16x8 qf[4];
;         {
;             u32x4 qw[4]; float ss = 0.f;
; #pragma unroll
;             for (int ks = 0; ks < 4; ++ks) { qw[ks] = *(const u32x4*)(QB + qrow * DM + hq * 64 + 16 * ks + 8 * hi);
;                 const unsigned ww[4] = {qw[ks].x, qw[ks].y, qw[ks].z, qw[ks].w};
; #pragma unroll
;                 for (int e = 0; e < 4; ++e) { const float lo = bf_lo(ww[e]), h2 = bf_hi(ww[e]); ss += lo * lo + h2 * h2; } }
;             ss += __shfl_xor(ss, 32);
;             const float rs = __builtin_amdgcn_rsqf(ss * (1.0f / 64.0f) + EPS) * 0.125f;
; #pragma unroll
;             for (int ks = 0; ks < 4; ++ks) { const f32x4 g0 = *(const f32x4*)(qnw + 16 * ks + 8 * hi), g1 = *(const f32x4*)(qnw + 16 * ks + 8 * hi + 4);
;                 u32x4 o; o.x = cvt_pk(bf_lo(qw[ks].x) * rs * g0.x, bf_hi(qw[ks].x) * rs * g0.y); o.y = cvt_pk(bf_lo(qw[ks].y) * rs * g0.z, bf_hi(qw[ks].y) * rs * g0.w);
;                 o.z = cvt_pk(bf_lo(qw[ks].z) * rs * g1.x, bf_hi(qw[ks].z) * rs * g1.y); o.w = cvt_pk(bf_lo(qw[ks].w) * rs * g1.z, bf_hi(qw[ks].w) * rs * g1.w);
;                 qf[ks] = __builtin_bit_cast(bf16x8, o); }
.LBB0_256:
	s_lshr_b32 s66, s62, 1
	s_and_b32 s67, s62, 1
	s_or_b32 s74, s66, s85
	s_or_b32 s71, s67, s65
	s_lshl_b32 s67, s74, 7
	s_add_u32 s67, s42, s67
	s_addc_u32 s68, s43, 0
	s_lshl_b32 s69, s71, 5
	s_or_b32 s67, s67, s69
	v_mov_b32_e32 v121, s68
	v_or_b32_e32 v120, s67, v130
	v_lshlrev_b64 v[122:123], 11, v[120:121]
	v_lshl_add_u64 v[12:13], v[116:117], 0, v[122:123]
	s_waitcnt lgkmcnt(0)
	s_waitcnt vmcnt(9)
	ds_read_b128 v[0:3], v238
	ds_read_b128 v[4:7], v238 offset:1024
	ds_read_b128 v[8:11], v238 offset:2048
	ds_read_b128 v[12:15], v238 offset:3072
	global_load_dwordx4 v[16:19], v[110:111], off offset:16
	global_load_dwordx4 v[20:23], v[110:111], off
	global_load_dwordx4 v[196:199], v[110:111], off offset:64
	global_load_dwordx4 v[200:203], v[110:111], off offset:80
	global_load_dwordx4 v[204:207], v[110:111], off offset:128
	global_load_dwordx4 v[208:211], v[110:111], off offset:144
	global_load_dwordx4 v[212:215], v[110:111], off offset:192
	global_load_dwordx4 v[216:219], v[110:111], off offset:208
	s_lshl_b32 s66, s66, 2
	s_or_b32 s75, s66, s71
	s_add_i32 s70, s75, 1
	s_add_i32 s69, s75, 2
	s_add_i32 s68, s75, 3
	s_waitcnt lgkmcnt(3)
	v_and_b32_e32 v25, 0xffff0000, v0
	v_and_b32_e32 v27, 0xffff0000, v1
	v_lshlrev_b32_e32 v24, 16, v0
	v_lshlrev_b32_e32 v26, 16, v1
	v_and_b32_e32 v29, 0xffff0000, v2
	s_waitcnt lgkmcnt(2)
	v_lshlrev_b32_e32 v32, 16, v4
	v_and_b32_e32 v33, 0xffff0000, v4
	v_lshlrev_b32_e32 v34, 16, v5
	v_and_b32_e32 v35, 0xffff0000, v5
	v_mul_f32_e32 v4, v25, v25
	v_mul_f32_e32 v5, v27, v27
	v_lshlrev_b32_e32 v28, 16, v2
	v_and_b32_e32 v31, 0xffff0000, v3
	v_lshlrev_b32_e32 v36, 16, v6
	v_and_b32_e32 v37, 0xffff0000, v6
	v_mul_f32_e32 v6, v29, v29
	v_fmac_f32_e32 v4, v24, v24
	v_fmac_f32_e32 v5, v26, v26
	v_lshlrev_b32_e32 v30, 16, v3
	v_lshlrev_b32_e32 v38, 16, v7
	v_and_b32_e32 v39, 0xffff0000, v7
	v_mul_f32_e32 v7, v31, v31
	v_fmac_f32_e32 v6, v28, v28
	v_add_f32_e32 v4, v4, v5
	v_mul_f32_e32 v48, v33, v33
	v_fmac_f32_e32 v7, v30, v30
	v_add_f32_e32 v4, v6, v4
	v_mul_f32_e32 v49, v35, v35
	v_fmac_f32_e32 v48, v32, v32
	v_add_f32_e32 v4, v7, v4
	v_mul_f32_e32 v50, v37, v37
	v_fmac_f32_e32 v49, v34, v34
	v_add_f32_e32 v4, v48, v4
	s_waitcnt lgkmcnt(1)
	v_and_b32_e32 v41, 0xffff0000, v8
	v_mul_f32_e32 v51, v39, v39
	v_fmac_f32_e32 v50, v36, v36
	v_add_f32_e32 v4, v49, v4
	v_lshlrev_b32_e32 v40, 16, v8
	v_and_b32_e32 v43, 0xffff0000, v9
	v_mul_f32_e32 v52, v41, v41
	v_fmac_f32_e32 v51, v38, v38
	v_add_f32_e32 v4, v50, v4
	v_lshlrev_b32_e32 v42, 16, v9
	v_and_b32_e32 v45, 0xffff0000, v10
	v_mul_f32_e32 v53, v43, v43
	v_fmac_f32_e32 v52, v40, v40
	v_add_f32_e32 v4, v51, v4
	v_lshlrev_b32_e32 v44, 16, v10
	v_and_b32_e32 v47, 0xffff0000, v11
	v_mul_f32_e32 v54, v45, v45
	v_fmac_f32_e32 v53, v42, v42
	v_add_f32_e32 v4, v52, v4
	v_lshlrev_b32_e32 v46, 16, v11
	s_waitcnt lgkmcnt(0)
	v_and_b32_e32 v11, 0xffff0000, v13
	v_and_b32_e32 v10, 0xffff0000, v12
	v_mul_f32_e32 v55, v47, v47
	v_fmac_f32_e32 v54, v44, v44
	v_add_f32_e32 v4, v53, v4
	v_lshlrev_b32_e32 v9, 16, v13
	v_lshlrev_b32_e32 v8, 16, v12
	v_pk_mul_f32 v[0:1], v[10:11], v[10:11]
	v_fmac_f32_e32 v55, v46, v46
	v_add_f32_e32 v4, v54, v4
	v_lshlrev_b32_e32 v13, 16, v15
	v_lshlrev_b32_e32 v12, 16, v14
	v_and_b32_e32 v15, 0xffff0000, v15
	v_and_b32_e32 v14, 0xffff0000, v14
	v_pk_fma_f32 v[0:1], v[8:9], v[8:9], v[0:1]
	v_add_f32_e32 v4, v55, v4
	v_pk_mul_f32 v[2:3], v[14:15], v[14:15]
	v_add_f32_e32 v0, v0, v4
	v_pk_fma_f32 v[2:3], v[12:13], v[12:13], v[2:3]
	v_add_f32_e32 v0, v1, v0
	v_add_f32_e32 v0, v2, v0
	v_add_f32_e32 v0, v3, v0
	ds_bpermute_b32 v1, v97, v0
	s_waitcnt lgkmcnt(0)
	v_add_f32_e32 v0, v0, v1
	v_fmamk_f32 v0, v0, 0x3c800000, v135
	v_rsq_f32_e32 v0, v0
	s_nop 0
	v_mul_f32_e32 v48, 0x3e000000, v0
	v_mul_f32_e32 v0, v48, v24
	v_mul_f32_e32 v1, v48, v25
	v_mul_f32_e32 v2, v48, v26
	v_mul_f32_e32 v3, v48, v27
	v_mul_f32_e32 v4, v48, v28
	v_mul_f32_e32 v5, v48, v29
	v_mul_f32_e32 v6, v48, v30
	v_mul_f32_e32 v7, v48, v31
	s_waitcnt vmcnt(0)
	v_mul_f32_e32 v0, v20, v0
	v_mul_f32_e32 v1, v21, v1
	v_mul_f32_e32 v2, v22, v2
	v_mul_f32_e32 v3, v23, v3
	v_mul_f32_e32 v4, v16, v4
	v_mul_f32_e32 v5, v17, v5
	v_mul_f32_e32 v6, v18, v6
	v_mul_f32_e32 v7, v19, v7
	v_cvt_pk_bf16_f32 v64, v0, v1
	v_cvt_pk_bf16_f32 v65, v2, v3
	v_cvt_pk_bf16_f32 v66, v4, v5
	v_cvt_pk_bf16_f32 v67, v6, v7
	v_mul_f32_e32 v16, v48, v32
	v_mul_f32_e32 v17, v48, v33
	v_mul_f32_e32 v18, v48, v34
	v_mul_f32_e32 v19, v48, v35
	v_mul_f32_e32 v20, v48, v36
	v_mul_f32_e32 v21, v48, v37
	v_mul_f32_e32 v22, v48, v38
	v_mul_f32_e32 v23, v48, v39
	v_mul_f32_e32 v8, v48, v8
	v_mul_f32_e32 v10, v48, v10
	v_mul_f32_e32 v9, v48, v9
	v_mul_f32_e32 v11, v48, v11
	v_mul_f32_e32 v12, v48, v12
	v_mul_f32_e32 v14, v48, v14
	v_mul_f32_e32 v13, v48, v13
	v_mul_f32_e32 v15, v48, v15
	v_mul_f32_e32 v0, v196, v16
	v_mul_f32_e32 v1, v197, v17
	v_mul_f32_e32 v2, v198, v18
	v_mul_f32_e32 v3, v199, v19
	v_mul_f32_e32 v4, v200, v20
	v_mul_f32_e32 v5, v201, v21
	v_mul_f32_e32 v6, v202, v22
	v_mul_f32_e32 v7, v203, v23
	v_cvt_pk_bf16_f32 v140, v0, v1
	v_cvt_pk_bf16_f32 v141, v2, v3
	v_cvt_pk_bf16_f32 v142, v4, v5
	v_cvt_pk_bf16_f32 v143, v6, v7
	v_mul_f32_e32 v16, v48, v40
	v_mul_f32_e32 v17, v48, v41
	v_mul_f32_e32 v18, v48, v42
	v_mul_f32_e32 v19, v48, v43
	v_mul_f32_e32 v20, v48, v44
	v_mul_f32_e32 v21, v48, v45
	v_mul_f32_e32 v22, v48, v46
	v_mul_f32_e32 v23, v48, v47
	v_mul_f32_e32 v0, v204, v16
	v_mul_f32_e32 v1, v205, v17
	v_mul_f32_e32 v2, v206, v18
	v_mul_f32_e32 v3, v207, v19
	v_mul_f32_e32 v4, v208, v20
	v_mul_f32_e32 v5, v209, v21
	v_mul_f32_e32 v6, v210, v22
	v_mul_f32_e32 v7, v211, v23
	v_cvt_pk_bf16_f32 v144, v0, v1
	v_cvt_pk_bf16_f32 v145, v2, v3
	v_cvt_pk_bf16_f32 v146, v4, v5
	v_cvt_pk_bf16_f32 v147, v6, v7
	v_mul_f32_e32 v0, v212, v8
	v_mul_f32_e32 v1, v213, v10
	v_mul_f32_e32 v2, v214, v9
	v_mul_f32_e32 v3, v215, v11
	v_mul_f32_e32 v4, v216, v12
	v_mul_f32_e32 v5, v217, v14
	v_mul_f32_e32 v6, v218, v13
	v_mul_f32_e32 v7, v219, v15
	s_cmp_lt_u32 s62, 3
	s_cbranch_scc0 .Lattn_nopf
	s_add_i32 s98, s62, 1
	s_lshr_b32 s99, s98, 1
	s_and_b32 s98, s98, 1
	s_or_b32 s99, s99, s85
	s_or_b32 s98, s98, s65
	s_lshl_b32 s99, s99, 7
	s_add_i32 s99, s99, s42
	s_lshl_b32 s98, s98, 5
	s_or_b32 s99, s99, s98
	v_or_b32_e32 v222, s99, v130
	v_lshlrev_b32_e32 v222, 11, v222
	v_mov_b32_e32 v223, 0
	v_lshl_add_u64 v[220:221], v[116:117], 0, v[222:223]
	s_add_i32 m0, s100, 0
	s_nop 0
	global_load_lds_dwordx4 v[220:221], off
	s_add_i32 m0, s100, 992
	s_nop 0
	global_load_lds_dwordx4 v[220:221], off offset:32
	s_add_i32 m0, s100, 1984
	s_nop 0
	global_load_lds_dwordx4 v[220:221], off offset:64
	s_add_i32 m0, s100, 2976
	s_nop 0
	global_load_lds_dwordx4 v[220:221], off offset:96
; #define LAS __attribute__((address_space(3)))
; __device__ __forceinline__ int crow(int r, int hi) { return (r & 3) + 8 * (r >> 2) + 4 * hi; }
; __device__ __forceinline__ void attn_item(const Args& a, LAS unsigned char* lds, int item, int wave, int lane) {
;     ...
;         f32x16 S[6];
; #pragma unroll
;         for (int i = 0; i < 6; ++i) {
;             const int kb = (i == 0) ? 0 : 4 * bl + qblk + i;
;             f32x16 acc;
; #pragma unroll
;             for (int e = 0; e < 16; ++e) acc[e] = 0.f;
; #pragma unroll
;             for (int ks = 0; ks < 4; ++ks) { const bf16x8 kf = *(const LAS bf16x8*)(lds + ATT_K_OFF + (kb * 32 + ql) * KP + (16 * ks + 8 * hi) * 2);
;                 acc = __builtin_amdgcn_mfma_f32_32x32x16_bf16(kf, qf[ks], acc, 0, 0, 0); }
;             S[i] = acc;
;         }
;         const float NEG = -INFINITY;
; #pragma unroll
;         for (int e = 0; e < 16; ++e) { const int kr = crow(e, hi);
;             if (kr >= 16) S[0][e] = NEG;
;             if (!(kr > ql)) S[1][e] = NEG;
;             if (!(kr <= ql)) S[5][e] = NEG; }
.Lattn_nopf:
	v_cvt_pk_bf16_f32 v148, v0, v1
	v_cvt_pk_bf16_f32 v149, v2, v3
	v_cvt_pk_bf16_f32 v150, v4, v5
	v_cvt_pk_bf16_f32 v151, v6, v7
	ds_read_b128 v[0:3], v136
	ds_read_b128 v[152:155], v136 offset:32
	v_lshl_or_b32 v4, s70, 5, v130
	v_mad_u64_u32 v[186:187], s[66:67], v4, s76, v[112:113]
	s_waitcnt lgkmcnt(1)
	v_mfma_f32_32x32x16_bf16 v[48:63], v[0:3], v[64:67], 0
	ds_read_b128 v[0:3], v186
	ds_read_b128 v[156:159], v186 offset:32
	v_lshl_or_b32 v4, s69, 5, v130
	v_mad_u64_u32 v[188:189], s[66:67], v4, s76, v[112:113]
	v_lshl_or_b32 v4, s68, 5, v130
	v_mad_u64_u32 v[190:191], s[66:67], v4, s76, v[112:113]
	s_waitcnt lgkmcnt(1)
	v_mfma_f32_32x32x16_bf16 v[80:95], v[0:3], v[64:67], 0
	ds_read_b128 v[0:3], v188
	ds_read_b128 v[170:173], v188 offset:32
	s_add_i32 s67, s75, 4
	v_lshl_or_b32 v4, s67, 5, v130
	v_mad_u64_u32 v[192:193], s[86:87], v4, s76, v[112:113]
	ds_read_b128 v[174:177], v190 offset:32
	s_waitcnt lgkmcnt(2)
	v_mfma_f32_32x32x16_bf16 v[32:47], v[0:3], v[64:67], 0
	ds_read_b128 v[0:3], v190
	s_add_i32 s66, s75, 5
	v_lshl_or_b32 v4, s66, 5, v130
	v_mad_u64_u32 v[194:195], s[86:87], v4, s76, v[112:113]
	ds_read_b128 v[178:181], v192 offset:32
	s_cmp_lg_u32 s74, 0
	s_waitcnt lgkmcnt(1)
	v_mfma_f32_32x32x16_bf16 v[16:31], v[0:3], v[64:67], 0
	ds_read_b128 v[0:3], v192
	ds_read_b128 v[68:71], v194
	ds_read_b128 v[182:185], v194 offset:32
	s_waitcnt lgkmcnt(2)
	v_mfma_f32_32x32x16_bf16 v[0:15], v[0:3], v[64:67], 0
	s_waitcnt lgkmcnt(1)
	v_mfma_f32_32x32x16_bf16 v[64:79], v[68:71], v[64:67], 0
	v_mfma_f32_32x32x16_bf16 v[48:63], v[152:155], v[140:143], v[48:63]
	v_mfma_f32_32x32x16_bf16 v[80:95], v[156:159], v[140:143], v[80:95]
	v_mfma_f32_32x32x16_bf16 v[32:47], v[170:173], v[140:143], v[32:47]
	v_mfma_f32_32x32x16_bf16 v[16:31], v[174:177], v[140:143], v[16:31]
	v_mfma_f32_32x32x16_bf16 v[0:15], v[178:181], v[140:143], v[0:15]
	s_waitcnt lgkmcnt(0)
	v_mfma_f32_32x32x16_bf16 v[64:79], v[182:185], v[140:143], v[64:79]
	ds_read_b128 v[140:143], v136 offset:64
	ds_read_b128 v[152:155], v136 offset:96
	s_waitcnt lgkmcnt(1)
	v_mfma_f32_32x32x16_bf16 v[48:63], v[140:143], v[144:147], v[48:63]
	ds_read_b128 v[140:143], v186 offset:64
	ds_read_b128 v[156:159], v186 offset:96
	s_waitcnt lgkmcnt(1)
	v_mfma_f32_32x32x16_bf16 v[80:95], v[140:143], v[144:147], v[80:95]
	ds_read_b128 v[140:143], v188 offset:64
	ds_read_b128 v[170:173], v188 offset:96
	s_waitcnt lgkmcnt(1)
	v_mfma_f32_32x32x16_bf16 v[32:47], v[140:143], v[144:147], v[32:47]
	ds_read_b128 v[140:143], v190 offset:64
	ds_read_b128 v[174:177], v190 offset:96
	s_waitcnt lgkmcnt(1)
	v_mfma_f32_32x32x16_bf16 v[16:31], v[140:143], v[144:147], v[16:31]
	ds_read_b128 v[140:143], v192 offset:64
	ds_read_b128 v[178:181], v192 offset:96
	s_waitcnt lgkmcnt(1)
	v_mfma_f32_32x32x16_bf16 v[0:15], v[140:143], v[144:147], v[0:15]
	ds_read_b128 v[140:143], v194 offset:64
	ds_read_b128 v[182:185], v194 offset:96
	s_waitcnt lgkmcnt(1)
	v_mfma_f32_32x32x16_bf16 v[64:79], v[140:143], v[144:147], v[64:79]
	v_mfma_f32_32x32x16_bf16 v[48:63], v[152:155], v[148:151], v[48:63]
	v_mfma_f32_32x32x16_bf16 v[80:95], v[156:159], v[148:151], v[80:95]
	v_mfma_f32_32x32x16_bf16 v[32:47], v[170:173], v[148:151], v[32:47]
	v_mfma_f32_32x32x16_bf16 v[16:31], v[174:177], v[148:151], v[16:31]
	v_mfma_f32_32x32x16_bf16 v[0:15], v[178:181], v[148:151], v[0:15]
	s_waitcnt lgkmcnt(0)
	v_mfma_f32_32x32x16_bf16 v[64:79], v[182:185], v[148:151], v[64:79]
	s_cbranch_scc0 .LBB0_258
	s_nop 5
	v_cndmask_b32_e64 v56, v137, v80, s[4:5]
	v_cndmask_b32_e64 v141, v81, v137, s[6:7]
	v_cndmask_b32_e64 v140, v137, v82, s[8:9]
	v_cndmask_b32_e64 v139, v137, v83, s[10:11]
	v_cndmask_b32_e64 v84, v137, v84, s[12:13]
	v_cndmask_b32_e64 v83, v137, v85, s[14:15]
	v_cndmask_b32_e64 v82, v137, v86, s[16:17]
	v_cndmask_b32_e64 v81, v137, v87, s[18:19]
	v_cndmask_b32_e64 v80, v137, v88, s[20:21]
	v_cndmask_b32_e64 v63, v137, v89, s[22:23]
	v_cndmask_b32_e64 v62, v137, v90, s[24:25]
	v_cndmask_b32_e64 v61, v137, v91, s[26:27]
	v_cndmask_b32_e64 v60, v137, v92, s[28:29]
	v_cndmask_b32_e64 v59, v137, v93, s[30:31]
	v_cndmask_b32_e64 v58, v137, v94, s[34:35]
	v_cndmask_b32_e64 v57, v137, v95, s[36:37]
	s_branch .LBB0_259

; template <bool FINAL>
; __device__ __forceinline__ void ssm_item(const Args& a, LAS unsigned char* lds, int item, int wave, int lane) {
;     ...
;         const f32x2 ec0 = Eb[c0 * 64 + j], ec1 = Eb[c0 * 64 + 32 + j];
;         s0r = (f32x2){c0r, fmaf(t0.x, c0r, fmaf(-t0.y, c0i, ec0.x))}; s0i = (f32x2){c0i, fmaf(t0.x, c0i, fmaf(t0.y, c0r, ec0.y))};
;         s1r = (f32x2){c1r, fmaf(t1.x, c1r, fmaf(-t1.y, c1i, ec1.x))}; s1i = (f32x2){c1i, fmaf(t1.x, c1i, fmaf(t1.y, c1r, ec1.y))};
;     }
;     const int bsel = (j >> 2) & 1, csel = j & 1, tt = ((j & 3) >> 1) + 2 * (j >> 3);
;     const size_t urow0 = meta ? (size_t)META_ROW + tt : (size_t)(b0 + bsel) * SEQ + (size_t)(c0 + csel) * CHUNK + tt;
;     const bf16* up = U + urow0 * DM + g * 16 + 8 * hi;
;     LAS unsigned char* sl = lds + wave * (32 * SP);
;     const int nsteps = meta ? 2 : CHUNK / 8;
;     const size_t erow = (size_t)b0 * SEQ + (size_t)(c0 + ((lane & 15) >> 3)) * CHUNK + (lane & 7);
;     const bf16* ue = U + erow * DM + g * 16 + 4 * (lane >> 4);
;     bf16* ze = Z + erow * DM + g * 16 + 4 * (lane >> 4);
;     bf16x8 uf = *(const bf16x8*)up;
;     u32x2 uu0 = (u32x2){0u, 0u}, uu1 = (u32x2){0u, 0u};
;     if (FINAL) { uu0 = *(const u32x2*)ue; uu1 = *(const u32x2*)(ue + (size_t)SEQ * DM); }
;     for (int st = 0; st < nsteps; ++st) {
;         bf16x8 ufn = uf; u32x2 un0 = uu0, un1 = uu1;
;         if (st + 1 < nsteps) { ufn = *(const bf16x8*)(up + (size_t)(st + 1) * 8 * DM);
;             if (FINAL) { un0 = *(const u32x2*)(ue + (size_t)(st + 1) * 8 * DM); un1 = *(const u32x2*)(ue + (size_t)(st + 1) * 8 * DM + (size_t)SEQ * DM); } }
;         f32x16 X[4];
; #pragma unroll
;         for (int k = 0; k < 4; ++k) { f32x16 z;
; #pragma unroll
;             for (int e = 0; e < 16; ++e) z[e] = 0.f;
;             X[k] = __builtin_amdgcn_mfma_f32_32x32x16_bf16(uf, bbf[k], z, 0, 0, 0); }
; #pragma unroll
;         for (int t = 0; t < 8; ++t) {
;             const f32x2 x0r = (f32x2){X[0][2 * t], X[0][2 * t + 1]}, x0i = (f32x2){X[1][2 * t], X[1][2 * t + 1]}, x1r = (f32x2){X[2][2 * t], X[2][2 * t + 1]}, x1i = (f32x2){X[3][2 * t], X[3][2 * t + 1]};
;             const f32x2 n0r = pk_fma(a0x, s0r, pk_fma(na0y, s0i, x0r)), n0i = pk_fma(a0x, s0i, pk_fma(a0y, s0r, x0i));
;             const f32x2 n1r = pk_fma(a1x, s1r, pk_fma(na1y, s1i, x1r)), n1i = pk_fma(a1x, s1i, pk_fma(a1y, s1r, x1i));
.LBB0_338:
	s_lshl_b32 s21, s20, 7
	s_lshl_b32 s22, s20, 6
	s_and_b32 s21, s21, 0x4000
	s_and_b32 s24, s22, 0x1e00
	s_lshl_b32 s22, s40, 4
	v_or_b32_e32 v6, s21, v161
	s_and_b32 s22, s22, 0x380
	v_or_b32_e32 v6, s24, v6
	s_add_i32 s22, s14, s22
	v_lshlrev_b32_e32 v106, 11, v6
	s_lshl_b32 s22, s22, 1
	s_mov_b32 s23, s11
	s_or_b32 s21, s24, s21
	v_lshl_add_u64 v[6:7], v[106:107], 0, s[22:23]
	v_add_lshl_u32 v106, s21, v241, 11
	s_lshl_b32 s21, s13, 6
	v_or_b32_e32 v14, s21, v130
	v_lshl_add_u64 v[8:9], v[106:107], 0, s[22:23]
	v_lshlrev_b32_e32 v106, 3, v14
	v_or_b32_e32 v16, s21, v104
	v_lshl_add_u64 v[14:15], v[4:5], 0, v[106:107]
	v_lshlrev_b32_e32 v106, 3, v16
	v_lshl_add_u64 v[4:5], v[4:5], 0, v[106:107]
	global_load_dwordx2 v[206:207], v[14:15], off
	global_load_dwordx2 v[204:205], v[4:5], off
	v_or_b32_e32 v4, s12, v163
	v_or_b32_e32 v5, s13, v165
	v_lshlrev_b32_e32 v4, 13, v4
	v_lshlrev_b32_e32 v5, 8, v5
	v_or_b32_e32 v14, s13, v169
	v_or3_b32 v4, v4, v5, v167
	s_lshl_b32 s12, s12, 13
	v_lshlrev_b32_e32 v14, 8, v14
	v_lshlrev_b32_e32 v106, 11, v4
	v_or3_b32 v16, v14, s12, v131
	v_lshl_add_u64 v[4:5], s[52:53], 0, v[106:107]
	v_lshlrev_b32_e32 v106, 11, v16
	s_lshl_b32 s10, s10, 1
	v_lshl_add_u64 v[14:15], s[52:53], 0, v[106:107]
	v_lshl_add_u64 v[4:5], v[4:5], 0, s[10:11]
	v_mov_b32_e32 v189, v107
	v_lshl_add_u64 v[14:15], v[14:15], 0, s[10:11]
	v_mov_b32_e32 v191, v107
	v_lshl_add_u64 v[4:5], v[4:5], 0, v[188:189]
	v_lshl_add_u64 v[14:15], v[14:15], 0, v[190:191]
	global_load_dwordx4 v[100:103], v[4:5], off
	global_load_dwordx2 v[218:219], v[14:15], off
	v_add_co_u32_e32 v4, vcc, 0x1000000, v14
	v_xor_b32_e32 v202, 0x80000000, v195
	s_nop 0
	v_addc_co_u32_e32 v5, vcc, 0, v15, vcc
	global_load_dwordx2 v[212:213], v[4:5], off
	v_xor_b32_e32 v196, 0x80000000, v193
	v_mov_b32_e32 v200, v195
	v_mov_b32_e32 v201, v195
	v_mov_b32_e32 v198, v193
	v_mov_b32_e32 v199, v193
	v_mov_b32_e32 v195, v194
	v_mov_b32_e32 v193, v192
	s_waitcnt vmcnt(6)
	v_mov_b32_e32 v216, v10
	s_waitcnt vmcnt(5)
	v_mov_b32_e32 v214, v12
	v_mov_b32_e32 v203, v202
	v_mov_b32_e32 v197, v196
	v_lshl_add_u64 v[208:209], v[114:115], 0, v[6:7]
	v_lshl_add_u64 v[210:211], v[116:117], 0, v[8:9]
	v_lshlrev_b32_e32 v106, 10, v16
	s_mov_b64 s[12:13], 0
	s_waitcnt vmcnt(4)
	v_fma_f32 v217, -v3, v11, v206
	v_fmac_f32_e32 v207, v3, v10
	s_waitcnt vmcnt(3)
	v_fma_f32 v215, -v1, v13, v204
	v_fmac_f32_e32 v205, v1, v12
	v_fmac_f32_e32 v217, v2, v10
	v_fmac_f32_e32 v207, v2, v11
	v_fmac_f32_e32 v215, v0, v12
	v_fmac_f32_e32 v205, v0, v13
	v_mov_b32_e32 v206, v11
	v_mov_b32_e32 v204, v13
	v_subrev_u32_e32 v137, s58, v208
	v_subrev_u32_e32 v139, s58, v210
	s_add_u32 s76, s58, 0xd104000
	s_addc_u32 s77, s59, 0
	s_add_u32 s78, s58, 0xe104000
	s_addc_u32 s79, s59, 0
	s_add_u32 s66, s58, 0xd108000
	s_addc_u32 s67, s59, 0
	s_add_u32 s68, s58, 0xe108000
	s_addc_u32 s69, s59, 0
	s_add_u32 s70, s58, 0x6e00000
	s_addc_u32 s71, s59, 0
	s_add_u32 s74, s58, 0x7e00000
	s_addc_u32 s75, s59, 0
	global_load_dwordx4 v[248:251], v139, s[58:59]
	s_lshl_b32 s80, s33, 10
	s_add_i32 s80, s80, 0x11000
	v_and_b32_e32 v147, 63, v224
	v_and_b32_e32 v141, 31, v147
	v_lshlrev_b32_e32 v141, 5, v141
	v_lshrrev_b32_e32 v145, 5, v147
	v_lshl_or_b32 v141, v145, 4, v141
	v_add_u32_e32 v141, s80, v141
	v_and_b32_e32 v143, 6, v147
	v_lshlrev_b32_e32 v143, 2, v143
	v_and_b32_e32 v145, 1, v147
	v_lshl_or_b32 v143, v145, 1, v143
	v_bfe_u32 v145, v147, 3, 1
	v_or_b32_e32 v143, v143, v145
	v_lshlrev_b32_e32 v143, 5, v143
	v_lshrrev_b32_e32 v145, 5, v147
	v_lshl_or_b32 v143, v145, 4, v143
	v_bfe_u32 v145, v147, 4, 1
	v_lshl_or_b32 v143, v145, 3, v143
	v_add_u32_e32 v143, s80, v143
	s_mov_b32 s62, 0xbdd2d3e8
	s_mov_b32 s63, 0xbdd2d3e8
	s_mov_b32 s64, 0x3f800000
	s_mov_b32 s65, 0x3f800000
	v_mov_b32_e32 v246, 0xc0135761
	v_add_u32_e32 v245, 0x440, v242
	v_add_u32_e32 v247, 0x880, v242
	v_add_u32_e32 v106, 0xcc0, v242
	v_add_u32_e32 v139, 0x4000, v139
	s_mov_b32 s12, 0
	s_waitcnt vmcnt(0)
.Lp3_step:
	s_waitcnt vmcnt(5)
	ds_write_b128 v141, v[100:103]
	ds_read_b64 v[252:253], v143
	ds_read_b64 v[254:255], v143 offset:128
	v_mfma_f32_32x32x16_bf16 v[0:15], v[100:103], v[88:91], 0
	v_mfma_f32_32x32x16_bf16 v[16:31], v[100:103], v[92:95], 0
	v_mfma_f32_32x32x16_bf16 v[32:47], v[100:103], v[96:99], 0
	v_mfma_f32_32x32x16_bf16 v[48:63], v[100:103], v[84:87], 0
	s_nop 15
	global_load_dwordx4 v[100:103], v139, s[58:59]
	v_add_u32_e32 v139, 0x4000, v139
	v_pk_fma_f32 v[0:1], v[202:203], v[206:207], v[0:1]
	v_pk_fma_f32 v[16:17], v[200:201], v[216:217], v[16:17]
	v_pk_fma_f32 v[32:33], v[196:197], v[204:205], v[32:33]
	v_pk_fma_f32 v[48:49], v[198:199], v[214:215], v[48:49]
	v_pk_fma_f32 v[0:1], v[194:195], v[216:217], v[0:1]
	v_pk_fma_f32 v[16:17], v[194:195], v[206:207], v[16:17]
	v_pk_fma_f32 v[32:33], v[192:193], v[214:215], v[32:33]
	v_pk_fma_f32 v[48:49], v[192:193], v[204:205], v[48:49]
	v_pk_fma_f32 v[2:3], v[202:203], v[16:17], v[2:3]
	v_pk_fma_f32 v[18:19], v[200:201], v[0:1], v[18:19]
	v_pk_fma_f32 v[34:35], v[196:197], v[48:49], v[34:35]
	v_pk_fma_f32 v[50:51], v[198:199], v[32:33], v[50:51]
	v_pk_fma_f32 v[2:3], v[194:195], v[0:1], v[2:3]
	v_pk_fma_f32 v[18:19], v[194:195], v[16:17], v[18:19]
	v_pk_fma_f32 v[34:35], v[192:193], v[32:33], v[34:35]
	v_pk_fma_f32 v[50:51], v[192:193], v[48:49], v[50:51]
	v_cvt_pk_bf16_f32 v119, v0, v16
	v_cvt_pk_bf16_f32 v121, v32, v48
	v_cvt_pk_bf16_f32 v123, v1, v17
	v_cvt_pk_bf16_f32 v125, v33, v49
	ds_write2_b32 v242, v119, v121 offset0:0 offset1:32
	ds_write2_b32 v247, v123, v125 offset0:0 offset1:32
	v_pk_fma_f32 v[4:5], v[202:203], v[18:19], v[4:5]
	v_pk_fma_f32 v[20:21], v[200:201], v[2:3], v[20:21]
; #define LAS __attribute__((address_space(3)))
; __device__ __forceinline__ unsigned cvt_pk(float lo, float hi) { unsigned r; asm volatile("v_cvt_pk_bf16_f32 %0, %1, %2" : "=v"(r) : "v"(lo), "v"(hi)); return r; }
; #define LDS_WAIT() asm volatile("s_waitcnt lgkmcnt(0)" ::: "memory")
; __device__ __forceinline__ f32x2 pk_fma(f32x2 a, f32x2 b, f32x2 c) { return __builtin_elementwise_fma(a, b, c); }
; template <bool FINAL>
; __device__ __forceinline__ void ssm_item(const Args& a, LAS unsigned char* lds, int item, int wave, int lane) {
;     ...
;         for (int t = 0; t < 8; ++t) {
;             const f32x2 x0r = (f32x2){X[0][2 * t], X[0][2 * t + 1]}, x0i = (f32x2){X[1][2 * t], X[1][2 * t + 1]}, x1r = (f32x2){X[2][2 * t], X[2][2 * t + 1]}, x1i = (f32x2){X[3][2 * t], X[3][2 * t + 1]};
;             const f32x2 n0r = pk_fma(a0x, s0r, pk_fma(na0y, s0i, x0r)), n0i = pk_fma(a0x, s0i, pk_fma(a0y, s0r, x0i));
;             const f32x2 n1r = pk_fma(a1x, s1r, pk_fma(na1y, s1i, x1r)), n1i = pk_fma(a1x, s1i, pk_fma(a1y, s1r, x1i));
;             s0r = n0r; s0i = n0i; s1r = n1r; s1i = n1i;
;             if (FINAL) {
;                 LAS unsigned char* r0 = sl + ((hi * 2 + 0) * 8 + t) * SP; LAS unsigned char* r1 = sl + ((hi * 2 + 1) * 8 + t) * SP;
;                 *(LAS unsigned*)(r0 + j * 4) = cvt_pk(n0r.x, n0i.x); *(LAS unsigned*)(r0 + (32 + j) * 4) = cvt_pk(n1r.x, n1i.x);
;                 *(LAS unsigned*)(r1 + j * 4) = cvt_pk(n0r.y, n0i.y); *(LAS unsigned*)(r1 + (32 + j) * 4) = cvt_pk(n1r.y, n1i.y); }
;         }
;         if (FINAL) {
;             LDS_WAIT(); asm volatile("" ::: "memory");
; #pragma unroll
;             for (int bh = 0; bh < 2; ++bh) {
;                 f32x4 Y = (f32x4){0.f, 0.f, 0.f, 0.f};
; #pragma unroll
;                 for (int k = 0; k < 4; ++k) { const bf16x8 sf = *(const LAS bf16x8*)(sl + (bh * 16 + (lane & 15)) * SP + (32 * k + 8 * (lane >> 4)) * 2);
;                     Y = __builtin_amdgcn_mfma_f32_16x16x32_bf16(cmf[k], sf, Y, 0, 0, 0); }
	v_pk_fma_f32 v[36:37], v[196:197], v[50:51], v[36:37]
	v_pk_fma_f32 v[52:53], v[198:199], v[34:35], v[52:53]
	v_pk_fma_f32 v[4:5], v[194:195], v[2:3], v[4:5]
	v_pk_fma_f32 v[20:21], v[194:195], v[18:19], v[20:21]
	v_pk_fma_f32 v[36:37], v[192:193], v[34:35], v[36:37]
	v_pk_fma_f32 v[52:53], v[192:193], v[50:51], v[52:53]
	v_cvt_pk_bf16_f32 v127, v2, v18
	v_cvt_pk_bf16_f32 v129, v34, v50
	v_cvt_pk_bf16_f32 v133, v3, v19
	v_cvt_pk_bf16_f32 v135, v35, v51
	ds_write2_b32 v242, v127, v129 offset0:68 offset1:100
	ds_write2_b32 v247, v133, v135 offset0:68 offset1:100
	v_pk_fma_f32 v[6:7], v[202:203], v[20:21], v[6:7]
	v_pk_fma_f32 v[22:23], v[200:201], v[4:5], v[22:23]
	v_pk_fma_f32 v[38:39], v[196:197], v[52:53], v[38:39]
	v_pk_fma_f32 v[54:55], v[198:199], v[36:37], v[54:55]
	v_pk_fma_f32 v[6:7], v[194:195], v[4:5], v[6:7]
	v_pk_fma_f32 v[22:23], v[194:195], v[20:21], v[22:23]
	v_pk_fma_f32 v[38:39], v[192:193], v[36:37], v[38:39]
	v_pk_fma_f32 v[54:55], v[192:193], v[52:53], v[54:55]
	v_cvt_pk_bf16_f32 v119, v4, v20
	v_cvt_pk_bf16_f32 v121, v36, v52
	v_cvt_pk_bf16_f32 v123, v5, v21
	v_cvt_pk_bf16_f32 v125, v37, v53
	ds_write2_b32 v242, v119, v121 offset0:136 offset1:168
	ds_write2_b32 v247, v123, v125 offset0:136 offset1:168
	v_pk_fma_f32 v[8:9], v[202:203], v[22:23], v[8:9]
	v_pk_fma_f32 v[24:25], v[200:201], v[6:7], v[24:25]
	v_pk_fma_f32 v[40:41], v[196:197], v[54:55], v[40:41]
	v_pk_fma_f32 v[56:57], v[198:199], v[38:39], v[56:57]
	v_pk_fma_f32 v[8:9], v[194:195], v[6:7], v[8:9]
	v_pk_fma_f32 v[24:25], v[194:195], v[22:23], v[24:25]
	v_pk_fma_f32 v[40:41], v[192:193], v[38:39], v[40:41]
	v_pk_fma_f32 v[56:57], v[192:193], v[54:55], v[56:57]
	v_cvt_pk_bf16_f32 v127, v6, v22
	v_cvt_pk_bf16_f32 v129, v38, v54
	v_cvt_pk_bf16_f32 v133, v7, v23
	v_cvt_pk_bf16_f32 v135, v39, v55
	ds_write2_b32 v242, v127, v129 offset0:204 offset1:236
	ds_write2_b32 v247, v133, v135 offset0:204 offset1:236
	v_pk_fma_f32 v[10:11], v[202:203], v[24:25], v[10:11]
	v_pk_fma_f32 v[26:27], v[200:201], v[8:9], v[26:27]
	v_pk_fma_f32 v[42:43], v[196:197], v[56:57], v[42:43]
	v_pk_fma_f32 v[58:59], v[198:199], v[40:41], v[58:59]
	v_pk_fma_f32 v[10:11], v[194:195], v[8:9], v[10:11]
	v_pk_fma_f32 v[26:27], v[194:195], v[24:25], v[26:27]
	v_pk_fma_f32 v[42:43], v[192:193], v[40:41], v[42:43]
	v_pk_fma_f32 v[58:59], v[192:193], v[56:57], v[58:59]
	v_cvt_pk_bf16_f32 v119, v8, v24
	v_cvt_pk_bf16_f32 v121, v40, v56
	v_cvt_pk_bf16_f32 v123, v9, v25
	v_cvt_pk_bf16_f32 v125, v41, v57
	ds_write2_b32 v245, v119, v121 offset0:0 offset1:32
	ds_write2_b32 v106, v123, v125 offset0:0 offset1:32
	v_pk_fma_f32 v[12:13], v[202:203], v[26:27], v[12:13]
	v_pk_fma_f32 v[28:29], v[200:201], v[10:11], v[28:29]
	v_pk_fma_f32 v[44:45], v[196:197], v[58:59], v[44:45]
	v_pk_fma_f32 v[60:61], v[198:199], v[42:43], v[60:61]
	v_pk_fma_f32 v[12:13], v[194:195], v[10:11], v[12:13]
	v_pk_fma_f32 v[28:29], v[194:195], v[26:27], v[28:29]
	v_pk_fma_f32 v[44:45], v[192:193], v[42:43], v[44:45]
	v_pk_fma_f32 v[60:61], v[192:193], v[58:59], v[60:61]
	v_cvt_pk_bf16_f32 v127, v10, v26
	v_cvt_pk_bf16_f32 v129, v42, v58
	v_cvt_pk_bf16_f32 v133, v11, v27
	v_cvt_pk_bf16_f32 v135, v43, v59
	ds_write2_b32 v245, v127, v129 offset0:68 offset1:100
	ds_write2_b32 v106, v133, v135 offset0:68 offset1:100
	v_pk_fma_f32 v[14:15], v[202:203], v[28:29], v[14:15]
	v_pk_fma_f32 v[30:31], v[200:201], v[12:13], v[30:31]
	v_pk_fma_f32 v[46:47], v[196:197], v[60:61], v[46:47]
	v_pk_fma_f32 v[62:63], v[198:199], v[44:45], v[62:63]
	v_pk_fma_f32 v[216:217], v[194:195], v[12:13], v[14:15]
	v_pk_fma_f32 v[206:207], v[194:195], v[28:29], v[30:31]
	v_pk_fma_f32 v[214:215], v[192:193], v[44:45], v[46:47]
	v_pk_fma_f32 v[204:205], v[192:193], v[60:61], v[62:63]
	v_cvt_pk_bf16_f32 v119, v12, v28
	v_cvt_pk_bf16_f32 v121, v44, v60
	v_cvt_pk_bf16_f32 v123, v13, v29
	v_cvt_pk_bf16_f32 v125, v45, v61
	ds_write2_b32 v245, v119, v121 offset0:136 offset1:168
	ds_write2_b32 v106, v123, v125 offset0:136 offset1:168
	v_cvt_pk_bf16_f32 v127, v216, v206
	v_cvt_pk_bf16_f32 v129, v214, v204
	v_cvt_pk_bf16_f32 v133, v217, v207
	v_cvt_pk_bf16_f32 v135, v215, v205
	ds_write2_b32 v245, v127, v129 offset0:204 offset1:236
	ds_write2_b32 v106, v133, v135 offset0:204 offset1:236
	s_waitcnt lgkmcnt(0)
	ds_read_b128 v[0:3], v244
	ds_read_b128 v[4:7], v244 offset:64
	ds_read_b128 v[8:11], v244 offset:128
	ds_read_b128 v[12:15], v244 offset:192
	ds_read_b128 v[16:19], v244 offset:4352
	ds_read_b128 v[20:23], v244 offset:4416
	ds_read_b128 v[24:27], v244 offset:4480
	ds_read_b128 v[28:31], v244 offset:4544
	s_waitcnt lgkmcnt(7)
	v_mfma_f32_16x16x32_bf16 v[32:35], v[80:83], v[0:3], 0
	s_waitcnt lgkmcnt(3)
	v_mfma_f32_16x16x32_bf16 v[36:39], v[80:83], v[16:19], 0
	s_waitcnt lgkmcnt(2)
	v_mfma_f32_16x16x32_bf16 v[32:35], v[76:79], v[4:7], v[32:35]
	v_mfma_f32_16x16x32_bf16 v[36:39], v[76:79], v[20:23], v[36:39]
	s_waitcnt lgkmcnt(1)
	v_mfma_f32_16x16x32_bf16 v[32:35], v[72:75], v[8:11], v[32:35]
	v_mfma_f32_16x16x32_bf16 v[36:39], v[72:75], v[24:27], v[36:39]
	s_waitcnt lgkmcnt(0)
; #define LAS __attribute__((address_space(3)))
; __device__ __forceinline__ unsigned cvt_pk(float lo, float hi) { unsigned r; asm volatile("v_cvt_pk_bf16_f32 %0, %1, %2" : "=v"(r) : "v"(lo), "v"(hi)); return r; }
; __device__ __forceinline__ float bf_lo(unsigned w) { return __uint_as_float(w << 16); }
; #define LDS_WAIT() asm volatile("s_waitcnt lgkmcnt(0)" ::: "memory")
; template <bool FINAL>
; __device__ __forceinline__ void ssm_item(const Args& a, LAS unsigned char* lds, int item, int wave, int lane) {
;     ...
;         for (int t = 0; t < 8; ++t) {
;             const f32x2 x0r = (f32x2){X[0][2 * t], X[0][2 * t + 1]}, x0i = (f32x2){X[1][2 * t], X[1][2 * t + 1]}, x1r = (f32x2){X[2][2 * t], X[2][2 * t + 1]}, x1i = (f32x2){X[3][2 * t], X[3][2 * t + 1]};
;             const f32x2 n0r = pk_fma(a0x, s0r, pk_fma(na0y, s0i, x0r)), n0i = pk_fma(a0x, s0i, pk_fma(a0y, s0r, x0i));
;             const f32x2 n1r = pk_fma(a1x, s1r, pk_fma(na1y, s1i, x1r)), n1i = pk_fma(a1x, s1i, pk_fma(a1y, s1r, x1i));
;             s0r = n0r; s0i = n0i; s1r = n1r; s1i = n1i;
;             if (FINAL) {
;                 LAS unsigned char* r0 = sl + ((hi * 2 + 0) * 8 + t) * SP; LAS unsigned char* r1 = sl + ((hi * 2 + 1) * 8 + t) * SP;
;                 *(LAS unsigned*)(r0 + j * 4) = cvt_pk(n0r.x, n0i.x); *(LAS unsigned*)(r0 + (32 + j) * 4) = cvt_pk(n1r.x, n1i.x);
;                 *(LAS unsigned*)(r1 + j * 4) = cvt_pk(n0r.y, n0i.y); *(LAS unsigned*)(r1 + (32 + j) * 4) = cvt_pk(n1r.y, n1i.y); }
;         }
;         if (FINAL) {
;             LDS_WAIT(); asm volatile("" ::: "memory");
; #pragma unroll
;             for (int bh = 0; bh < 2; ++bh) {
;                 f32x4 Y = (f32x4){0.f, 0.f, 0.f, 0.f};
; #pragma unroll
;                 for (int k = 0; k < 4; ++k) { const bf16x8 sf = *(const LAS bf16x8*)(sl + (bh * 16 + (lane & 15)) * SP + (32 * k + 8 * (lane >> 4)) * 2);
;                     Y = __builtin_amdgcn_mfma_f32_16x16x32_bf16(cmf[k], sf, Y, 0, 0, 0); }
;                 const u32x2 uu = bh ? uu1 : uu0;
;                 const float y0 = Y[0] + dsk.x * bf_lo(uu.x), y1 = Y[1] + dsk.y * bf_hi(uu.x), y2 = Y[2] + dsk.z * bf_lo(uu.y), y3 = Y[3] + dsk.w * bf_hi(uu.y);
;                 u32x2 w; w.x = cvt_pk(gelu_tanh(y0), gelu_tanh(y1)); w.y = cvt_pk(gelu_tanh(y2), gelu_tanh(y3));
;                 *(u32x2*)(ze + (size_t)st * 8 * DM + (size_t)bh * SEQ * DM) = w;
	v_mfma_f32_16x16x32_bf16 v[32:35], v[68:71], v[12:15], v[32:35]
	v_mfma_f32_16x16x32_bf16 v[36:39], v[68:71], v[28:31], v[36:39]
	v_lshlrev_b32_e32 v48, 16, v252
	v_and_b32_e32 v49, 0xffff0000, v252
	v_lshlrev_b32_e32 v50, 16, v253
	v_and_b32_e32 v51, 0xffff0000, v253
	v_lshlrev_b32_e32 v52, 16, v254
	v_and_b32_e32 v53, 0xffff0000, v254
	v_lshlrev_b32_e32 v54, 16, v255
	v_and_b32_e32 v55, 0xffff0000, v255
	s_nop 1
	v_pk_fma_f32 v[32:33], v[64:65], v[48:49], v[32:33]
	v_pk_fma_f32 v[34:35], v[66:67], v[50:51], v[34:35]
	v_pk_fma_f32 v[36:37], v[64:65], v[52:53], v[36:37]
	v_pk_fma_f32 v[38:39], v[66:67], v[54:55], v[38:39]
	v_pk_mul_f32 v[40:41], v[32:33], v[32:33]
	v_pk_mul_f32 v[42:43], v[34:35], v[34:35]
	v_pk_mul_f32 v[44:45], v[36:37], v[36:37]
	v_pk_mul_f32 v[46:47], v[38:39], v[38:39]
	v_pk_fma_f32 v[40:41], v[40:41], s[62:63], v[246:247] op_sel_hi:[1,1,0]
	v_pk_fma_f32 v[42:43], v[42:43], s[62:63], v[246:247] op_sel_hi:[1,1,0]
	v_pk_fma_f32 v[44:45], v[44:45], s[62:63], v[246:247] op_sel_hi:[1,1,0]
	v_pk_fma_f32 v[46:47], v[46:47], s[62:63], v[246:247] op_sel_hi:[1,1,0]
	v_pk_mul_f32 v[40:41], v[32:33], v[40:41]
	v_pk_mul_f32 v[42:43], v[34:35], v[42:43]
	v_pk_mul_f32 v[44:45], v[36:37], v[44:45]
	v_pk_mul_f32 v[46:47], v[38:39], v[46:47]
	v_exp_f32_e32 v40, v40
	v_exp_f32_e32 v41, v41
	v_exp_f32_e32 v42, v42
	v_exp_f32_e32 v43, v43
	v_exp_f32_e32 v44, v44
	v_exp_f32_e32 v45, v45
	v_exp_f32_e32 v46, v46
	v_exp_f32_e32 v47, v47
	v_pk_add_f32 v[40:41], v[40:41], s[64:65]
	v_pk_add_f32 v[42:43], v[42:43], s[64:65]
	v_pk_add_f32 v[44:45], v[44:45], s[64:65]
	v_pk_add_f32 v[46:47], v[46:47], s[64:65]
	v_rcp_f32_e32 v40, v40
	v_rcp_f32_e32 v41, v41
	v_rcp_f32_e32 v42, v42
	v_rcp_f32_e32 v43, v43
	v_rcp_f32_e32 v44, v44
	v_rcp_f32_e32 v45, v45
	v_rcp_f32_e32 v46, v46
	v_rcp_f32_e32 v47, v47
	v_pk_mul_f32 v[32:33], v[32:33], v[40:41]
	v_pk_mul_f32 v[34:35], v[34:35], v[42:43]
	v_pk_mul_f32 v[36:37], v[36:37], v[44:45]
	v_pk_mul_f32 v[38:39], v[38:39], v[46:47]
	s_nop 0
	v_cvt_pk_bf16_f32 v40, v32, v33
	v_cvt_pk_bf16_f32 v41, v34, v35
	v_cvt_pk_bf16_f32 v42, v36, v37
	v_cvt_pk_bf16_f32 v43, v38, v39
	global_store_dwordx2 v137, v[40:41], s[70:71]
	global_store_dwordx2 v137, v[42:43], s[74:75]
	v_add_u32_e32 v137, 0x4000, v137
	s_waitcnt vmcnt(5)
	ds_write_b128 v141, v[248:251]
	ds_read_b64 v[252:253], v143
	ds_read_b64 v[254:255], v143 offset:128
	v_mfma_f32_32x32x16_bf16 v[0:15], v[248:251], v[88:91], 0
	v_mfma_f32_32x32x16_bf16 v[16:31], v[248:251], v[92:95], 0
	v_mfma_f32_32x32x16_bf16 v[32:47], v[248:251], v[96:99], 0
	v_mfma_f32_32x32x16_bf16 v[48:63], v[248:251], v[84:87], 0
	s_nop 15
	global_load_dwordx4 v[248:251], v139, s[58:59]
	v_add_u32_e32 v139, 0x4000, v139
	v_pk_fma_f32 v[0:1], v[202:203], v[206:207], v[0:1]
	v_pk_fma_f32 v[16:17], v[200:201], v[216:217], v[16:17]
	v_pk_fma_f32 v[32:33], v[196:197], v[204:205], v[32:33]
	v_pk_fma_f32 v[48:49], v[198:199], v[214:215], v[48:49]
	v_pk_fma_f32 v[0:1], v[194:195], v[216:217], v[0:1]
	v_pk_fma_f32 v[16:17], v[194:195], v[206:207], v[16:17]
	v_pk_fma_f32 v[32:33], v[192:193], v[214:215], v[32:33]
	v_pk_fma_f32 v[48:49], v[192:193], v[204:205], v[48:49]
	v_pk_fma_f32 v[2:3], v[202:203], v[16:17], v[2:3]
	v_pk_fma_f32 v[18:19], v[200:201], v[0:1], v[18:19]
	v_pk_fma_f32 v[34:35], v[196:197], v[48:49], v[34:35]
	v_pk_fma_f32 v[50:51], v[198:199], v[32:33], v[50:51]
	v_pk_fma_f32 v[2:3], v[194:195], v[0:1], v[2:3]
	v_pk_fma_f32 v[18:19], v[194:195], v[16:17], v[18:19]
	v_pk_fma_f32 v[34:35], v[192:193], v[32:33], v[34:35]
	v_pk_fma_f32 v[50:51], v[192:193], v[48:49], v[50:51]
	v_cvt_pk_bf16_f32 v119, v0, v16
	v_cvt_pk_bf16_f32 v121, v32, v48
	v_cvt_pk_bf16_f32 v123, v1, v17
	v_cvt_pk_bf16_f32 v125, v33, v49
	ds_write2_b32 v242, v119, v121 offset0:0 offset1:32
	ds_write2_b32 v247, v123, v125 offset0:0 offset1:32
	v_pk_fma_f32 v[4:5], v[202:203], v[18:19], v[4:5]
	v_pk_fma_f32 v[20:21], v[200:201], v[2:3], v[20:21]
	v_pk_fma_f32 v[36:37], v[196:197], v[50:51], v[36:37]
	v_pk_fma_f32 v[52:53], v[198:199], v[34:35], v[52:53]
	v_pk_fma_f32 v[4:5], v[194:195], v[2:3], v[4:5]
	v_pk_fma_f32 v[20:21], v[194:195], v[18:19], v[20:21]
	v_pk_fma_f32 v[36:37], v[192:193], v[34:35], v[36:37]
	v_pk_fma_f32 v[52:53], v[192:193], v[50:51], v[52:53]
	v_cvt_pk_bf16_f32 v127, v2, v18
	v_cvt_pk_bf16_f32 v129, v34, v50
	v_cvt_pk_bf16_f32 v133, v3, v19
	v_cvt_pk_bf16_f32 v135, v35, v51
	ds_write2_b32 v242, v127, v129 offset0:68 offset1:100
	ds_write2_b32 v247, v133, v135 offset0:68 offset1:100
	v_pk_fma_f32 v[6:7], v[202:203], v[20:21], v[6:7]
	v_pk_fma_f32 v[22:23], v[200:201], v[4:5], v[22:23]
	v_pk_fma_f32 v[38:39], v[196:197], v[52:53], v[38:39]
	v_pk_fma_f32 v[54:55], v[198:199], v[36:37], v[54:55]
	v_pk_fma_f32 v[6:7], v[194:195], v[4:5], v[6:7]
	v_pk_fma_f32 v[22:23], v[194:195], v[20:21], v[22:23]
	v_pk_fma_f32 v[38:39], v[192:193], v[36:37], v[38:39]
	v_pk_fma_f32 v[54:55], v[192:193], v[52:53], v[54:55]
	v_cvt_pk_bf16_f32 v119, v4, v20
	v_cvt_pk_bf16_f32 v121, v36, v52
	v_cvt_pk_bf16_f32 v123, v5, v21
	v_cvt_pk_bf16_f32 v125, v37, v53
	ds_write2_b32 v242, v119, v121 offset0:136 offset1:168
	ds_write2_b32 v247, v123, v125 offset0:136 offset1:168
	v_pk_fma_f32 v[8:9], v[202:203], v[22:23], v[8:9]
	v_pk_fma_f32 v[24:25], v[200:201], v[6:7], v[24:25]
	v_pk_fma_f32 v[40:41], v[196:197], v[54:55], v[40:41]
	v_pk_fma_f32 v[56:57], v[198:199], v[38:39], v[56:57]
	v_pk_fma_f32 v[8:9], v[194:195], v[6:7], v[8:9]
	v_pk_fma_f32 v[24:25], v[194:195], v[22:23], v[24:25]
	v_pk_fma_f32 v[40:41], v[192:193], v[38:39], v[40:41]
	v_pk_fma_f32 v[56:57], v[192:193], v[54:55], v[56:57]
	v_cvt_pk_bf16_f32 v127, v6, v22
; #define LAS __attribute__((address_space(3)))
; __device__ __forceinline__ unsigned cvt_pk(float lo, float hi) { unsigned r; asm volatile("v_cvt_pk_bf16_f32 %0, %1, %2" : "=v"(r) : "v"(lo), "v"(hi)); return r; }
; template <bool FINAL>
; __device__ __forceinline__ void ssm_item(const Args& a, LAS unsigned char* lds, int item, int wave, int lane) {
;     ...
;         for (int t = 0; t < 8; ++t) {
;             const f32x2 x0r = (f32x2){X[0][2 * t], X[0][2 * t + 1]}, x0i = (f32x2){X[1][2 * t], X[1][2 * t + 1]}, x1r = (f32x2){X[2][2 * t], X[2][2 * t + 1]}, x1i = (f32x2){X[3][2 * t], X[3][2 * t + 1]};
;             const f32x2 n0r = pk_fma(a0x, s0r, pk_fma(na0y, s0i, x0r)), n0i = pk_fma(a0x, s0i, pk_fma(a0y, s0r, x0i));
;             const f32x2 n1r = pk_fma(a1x, s1r, pk_fma(na1y, s1i, x1r)), n1i = pk_fma(a1x, s1i, pk_fma(a1y, s1r, x1i));
;             s0r = n0r; s0i = n0i; s1r = n1r; s1i = n1i;
;             if (FINAL) {
;                 LAS unsigned char* r0 = sl + ((hi * 2 + 0) * 8 + t) * SP; LAS unsigned char* r1 = sl + ((hi * 2 + 1) * 8 + t) * SP;
;                 *(LAS unsigned*)(r0 + j * 4) = cvt_pk(n0r.x, n0i.x); *(LAS unsigned*)(r0 + (32 + j) * 4) = cvt_pk(n1r.x, n1i.x);
;                 *(LAS unsigned*)(r1 + j * 4) = cvt_pk(n0r.y, n0i.y); *(LAS unsigned*)(r1 + (32 + j) * 4) = cvt_pk(n1r.y, n1i.y); }
;         }
;         if (FINAL) {
;             LDS_WAIT(); asm volatile("" ::: "memory");
; #pragma unroll
;             for (int bh = 0; bh < 2; ++bh) {
;                 f32x4 Y = (f32x4){0.f, 0.f, 0.f, 0.f};
; #pragma unroll
;                 for (int k = 0; k < 4; ++k) { const bf16x8 sf = *(const LAS bf16x8*)(sl + (bh * 16 + (lane & 15)) * SP + (32 * k + 8 * (lane >> 4)) * 2);
;                     Y = __builtin_amdgcn_mfma_f32_16x16x32_bf16(cmf[k], sf, Y, 0, 0, 0); }
;                 const u32x2 uu = bh ? uu1 : uu0;
;                 const float y0 = Y[0] + dsk.x * bf_lo(uu.x), y1 = Y[1] + dsk.y * bf_hi(uu.x), y2 = Y[2] + dsk.z * bf_lo(uu.y), y3 = Y[3] + dsk.w * bf_hi(uu.y);
;                 u32x2 w; w.x = cvt_pk(gelu_tanh(y0), gelu_tanh(y1)); w.y = cvt_pk(gelu_tanh(y2), gelu_tanh(y3));
;                 *(u32x2*)(ze + (size_t)st * 8 * DM + (size_t)bh * SEQ * DM) = w;
;             }
;             LDS_WAIT(); asm volatile("" ::: "memory");
;         }
;         uf = ufn; uu0 = un0; uu1 = un1;
;     }
	v_cvt_pk_bf16_f32 v129, v38, v54
	v_cvt_pk_bf16_f32 v133, v7, v23
	v_cvt_pk_bf16_f32 v135, v39, v55
	ds_write2_b32 v242, v127, v129 offset0:204 offset1:236
	ds_write2_b32 v247, v133, v135 offset0:204 offset1:236
	v_pk_fma_f32 v[10:11], v[202:203], v[24:25], v[10:11]
	v_pk_fma_f32 v[26:27], v[200:201], v[8:9], v[26:27]
	v_pk_fma_f32 v[42:43], v[196:197], v[56:57], v[42:43]
	v_pk_fma_f32 v[58:59], v[198:199], v[40:41], v[58:59]
	v_pk_fma_f32 v[10:11], v[194:195], v[8:9], v[10:11]
	v_pk_fma_f32 v[26:27], v[194:195], v[24:25], v[26:27]
	v_pk_fma_f32 v[42:43], v[192:193], v[40:41], v[42:43]
	v_pk_fma_f32 v[58:59], v[192:193], v[56:57], v[58:59]
	v_cvt_pk_bf16_f32 v119, v8, v24
	v_cvt_pk_bf16_f32 v121, v40, v56
	v_cvt_pk_bf16_f32 v123, v9, v25
	v_cvt_pk_bf16_f32 v125, v41, v57
	ds_write2_b32 v245, v119, v121 offset0:0 offset1:32
	ds_write2_b32 v106, v123, v125 offset0:0 offset1:32
	v_pk_fma_f32 v[12:13], v[202:203], v[26:27], v[12:13]
	v_pk_fma_f32 v[28:29], v[200:201], v[10:11], v[28:29]
	v_pk_fma_f32 v[44:45], v[196:197], v[58:59], v[44:45]
	v_pk_fma_f32 v[60:61], v[198:199], v[42:43], v[60:61]
	v_pk_fma_f32 v[12:13], v[194:195], v[10:11], v[12:13]
	v_pk_fma_f32 v[28:29], v[194:195], v[26:27], v[28:29]
	v_pk_fma_f32 v[44:45], v[192:193], v[42:43], v[44:45]
	v_pk_fma_f32 v[60:61], v[192:193], v[58:59], v[60:61]
	v_cvt_pk_bf16_f32 v127, v10, v26
	v_cvt_pk_bf16_f32 v129, v42, v58
	v_cvt_pk_bf16_f32 v133, v11, v27
	v_cvt_pk_bf16_f32 v135, v43, v59
	ds_write2_b32 v245, v127, v129 offset0:68 offset1:100
	ds_write2_b32 v106, v133, v135 offset0:68 offset1:100
	v_pk_fma_f32 v[14:15], v[202:203], v[28:29], v[14:15]
	v_pk_fma_f32 v[30:31], v[200:201], v[12:13], v[30:31]
	v_pk_fma_f32 v[46:47], v[196:197], v[60:61], v[46:47]
	v_pk_fma_f32 v[62:63], v[198:199], v[44:45], v[62:63]
	v_pk_fma_f32 v[216:217], v[194:195], v[12:13], v[14:15]
	v_pk_fma_f32 v[206:207], v[194:195], v[28:29], v[30:31]
	v_pk_fma_f32 v[214:215], v[192:193], v[44:45], v[46:47]
	v_pk_fma_f32 v[204:205], v[192:193], v[60:61], v[62:63]
	v_cvt_pk_bf16_f32 v119, v12, v28
	v_cvt_pk_bf16_f32 v121, v44, v60
	v_cvt_pk_bf16_f32 v123, v13, v29
	v_cvt_pk_bf16_f32 v125, v45, v61
	ds_write2_b32 v245, v119, v121 offset0:136 offset1:168
	ds_write2_b32 v106, v123, v125 offset0:136 offset1:168
	v_cvt_pk_bf16_f32 v127, v216, v206
	v_cvt_pk_bf16_f32 v129, v214, v204
	v_cvt_pk_bf16_f32 v133, v217, v207
	v_cvt_pk_bf16_f32 v135, v215, v205
	ds_write2_b32 v245, v127, v129 offset0:204 offset1:236
	ds_write2_b32 v106, v133, v135 offset0:204 offset1:236
	s_waitcnt lgkmcnt(0)
	ds_read_b128 v[0:3], v244
	ds_read_b128 v[4:7], v244 offset:64
	ds_read_b128 v[8:11], v244 offset:128
	ds_read_b128 v[12:15], v244 offset:192
	ds_read_b128 v[16:19], v244 offset:4352
	ds_read_b128 v[20:23], v244 offset:4416
	ds_read_b128 v[24:27], v244 offset:4480
	ds_read_b128 v[28:31], v244 offset:4544
	s_waitcnt lgkmcnt(7)
	v_mfma_f32_16x16x32_bf16 v[32:35], v[80:83], v[0:3], 0
	s_waitcnt lgkmcnt(3)
	v_mfma_f32_16x16x32_bf16 v[36:39], v[80:83], v[16:19], 0
	s_waitcnt lgkmcnt(2)
	v_mfma_f32_16x16x32_bf16 v[32:35], v[76:79], v[4:7], v[32:35]
	v_mfma_f32_16x16x32_bf16 v[36:39], v[76:79], v[20:23], v[36:39]
	s_waitcnt lgkmcnt(1)
	v_mfma_f32_16x16x32_bf16 v[32:35], v[72:75], v[8:11], v[32:35]
	v_mfma_f32_16x16x32_bf16 v[36:39], v[72:75], v[24:27], v[36:39]
	s_waitcnt lgkmcnt(0)
	v_mfma_f32_16x16x32_bf16 v[32:35], v[68:71], v[12:15], v[32:35]
	v_mfma_f32_16x16x32_bf16 v[36:39], v[68:71], v[28:31], v[36:39]
	v_lshlrev_b32_e32 v48, 16, v252
	v_and_b32_e32 v49, 0xffff0000, v252
	v_lshlrev_b32_e32 v50, 16, v253
	v_and_b32_e32 v51, 0xffff0000, v253
	v_lshlrev_b32_e32 v52, 16, v254
	v_and_b32_e32 v53, 0xffff0000, v254
	v_lshlrev_b32_e32 v54, 16, v255
	v_and_b32_e32 v55, 0xffff0000, v255
	s_nop 1
	v_pk_fma_f32 v[32:33], v[64:65], v[48:49], v[32:33]
	v_pk_fma_f32 v[34:35], v[66:67], v[50:51], v[34:35]
	v_pk_fma_f32 v[36:37], v[64:65], v[52:53], v[36:37]
	v_pk_fma_f32 v[38:39], v[66:67], v[54:55], v[38:39]
	v_pk_mul_f32 v[40:41], v[32:33], v[32:33]
	v_pk_mul_f32 v[42:43], v[34:35], v[34:35]
	v_pk_mul_f32 v[44:45], v[36:37], v[36:37]
	v_pk_mul_f32 v[46:47], v[38:39], v[38:39]
	v_pk_fma_f32 v[40:41], v[40:41], s[62:63], v[246:247] op_sel_hi:[1,1,0]
	v_pk_fma_f32 v[42:43], v[42:43], s[62:63], v[246:247] op_sel_hi:[1,1,0]
	v_pk_fma_f32 v[44:45], v[44:45], s[62:63], v[246:247] op_sel_hi:[1,1,0]
	v_pk_fma_f32 v[46:47], v[46:47], s[62:63], v[246:247] op_sel_hi:[1,1,0]
	v_pk_mul_f32 v[40:41], v[32:33], v[40:41]
	v_pk_mul_f32 v[42:43], v[34:35], v[42:43]
	v_pk_mul_f32 v[44:45], v[36:37], v[44:45]
	v_pk_mul_f32 v[46:47], v[38:39], v[46:47]
	v_exp_f32_e32 v40, v40
	v_exp_f32_e32 v41, v41
	v_exp_f32_e32 v42, v42
	v_exp_f32_e32 v43, v43
	v_exp_f32_e32 v44, v44
	v_exp_f32_e32 v45, v45
	v_exp_f32_e32 v46, v46
	v_exp_f32_e32 v47, v47
	v_pk_add_f32 v[40:41], v[40:41], s[64:65]
	v_pk_add_f32 v[42:43], v[42:43], s[64:65]
	v_pk_add_f32 v[44:45], v[44:45], s[64:65]
	v_pk_add_f32 v[46:47], v[46:47], s[64:65]
	v_rcp_f32_e32 v40, v40
	v_rcp_f32_e32 v41, v41
	v_rcp_f32_e32 v42, v42
	v_rcp_f32_e32 v43, v43
	v_rcp_f32_e32 v44, v44
	v_rcp_f32_e32 v45, v45
	v_rcp_f32_e32 v46, v46
	v_rcp_f32_e32 v47, v47
	v_pk_mul_f32 v[32:33], v[32:33], v[40:41]
	v_pk_mul_f32 v[34:35], v[34:35], v[42:43]
	v_pk_mul_f32 v[36:37], v[36:37], v[44:45]
	v_pk_mul_f32 v[38:39], v[38:39], v[46:47]
	s_add_i32 s12, s12, 1
	s_cmp_lg_u32 s12, 16
	v_cvt_pk_bf16_f32 v40, v32, v33
	v_cvt_pk_bf16_f32 v41, v34, v35
	v_cvt_pk_bf16_f32 v42, v36, v37
	v_cvt_pk_bf16_f32 v43, v38, v39
	global_store_dwordx2 v137, v[40:41], s[70:71]
	global_store_dwordx2 v137, v[42:43], s[74:75]
	v_add_u32_e32 v137, 0x4000, v137
	s_cbranch_scc1 .Lp3_step
	s_add_i32 s20, s20, s92
	s_add_i32 s40, s40, s96
	s_cmpk_gt_i32 s20, 0xff
	s_cbranch_scc0 .LBB0_328

; __global__ void __launch_bounds__(NTHREADS, 2) mk_fwd(Args a) {
	.amdhsa_kernel _Z6mk_fwd4Args
		.amdhsa_group_segment_fixed_size 0
		.amdhsa_private_segment_fixed_size 0
		.amdhsa_kernarg_size 456
		.amdhsa_user_sgpr_count 2
		.amdhsa_user_sgpr_dispatch_ptr 0
		.amdhsa_user_sgpr_queue_ptr 0
		.amdhsa_user_sgpr_kernarg_segment_ptr 1
		.amdhsa_user_sgpr_dispatch_id 0
		.amdhsa_user_sgpr_kernarg_preload_length 0
		.amdhsa_user_sgpr_kernarg_preload_offset 0
		.amdhsa_user_sgpr_private_segment_size 0
		.amdhsa_uses_dynamic_stack 0
		.amdhsa_enable_private_segment 0
		.amdhsa_system_sgpr_workgroup_id_x 1
		.amdhsa_system_sgpr_workgroup_id_y 0
		.amdhsa_system_sgpr_workgroup_id_z 0
		.amdhsa_system_sgpr_workgroup_info 0
		.amdhsa_system_vgpr_workitem_id 2
		.amdhsa_next_free_vgpr 256
		.amdhsa_next_free_sgpr 102
		.amdhsa_accum_offset 256
		.amdhsa_reserve_vcc 1
		.amdhsa_float_round_mode_32 0
		.amdhsa_float_round_mode_16_64 0
		.amdhsa_float_denorm_mode_32 3
		.amdhsa_float_denorm_mode_16_64 3
		.amdhsa_dx10_clamp 1
		.amdhsa_ieee_mode 1
		.amdhsa_fp16_overflow 0
		.amdhsa_tg_split 0
		.amdhsa_exception_fp_ieee_invalid_op 0
		.amdhsa_exception_fp_denorm_src 0
		.amdhsa_exception_fp_ieee_div_zero 0
		.amdhsa_exception_fp_ieee_overflow 0
		.amdhsa_exception_fp_ieee_underflow 0
		.amdhsa_exception_fp_ieee_inexact 0
		.amdhsa_exception_int_div_zero 0
	.end_amdhsa_kernel

; __global__ void __launch_bounds__(NTHREADS, 2) mk_fwd(Args a) {
amdhsa.kernels:
  - .agpr_count:     0
    .args:
      - .offset:         0
        .size:           200
        .value_kind:     by_value
      - .offset:         200
        .size:           4
        .value_kind:     hidden_block_count_x
      - .offset:         204
        .size:           4
        .value_kind:     hidden_block_count_y
      - .offset:         208
        .size:           4
        .value_kind:     hidden_block_count_z
      - .offset:         212
        .size:           2
        .value_kind:     hidden_group_size_x
      - .offset:         214
        .size:           2
        .value_kind:     hidden_group_size_y
      - .offset:         216
        .size:           2
        .value_kind:     hidden_group_size_z
      - .offset:         218
        .size:           2
        .value_kind:     hidden_remainder_x
      - .offset:         220
        .size:           2
        .value_kind:     hidden_remainder_y
      - .offset:         222
        .size:           2
        .value_kind:     hidden_remainder_z
      - .offset:         240
        .size:           8
        .value_kind:     hidden_global_offset_x
      - .offset:         248
        .size:           8
        .value_kind:     hidden_global_offset_y
      - .offset:         256
        .size:           8
        .value_kind:     hidden_global_offset_z
      - .offset:         264
        .size:           2
        .value_kind:     hidden_grid_dims
      - .offset:         288
        .size:           8
        .value_kind:     hidden_multigrid_sync_arg
      - .offset:         320
        .size:           4
        .value_kind:     hidden_dynamic_lds_size
    .group_segment_fixed_size: 0
    .kernarg_segment_align: 8
    .kernarg_segment_size: 456
    .language:       OpenCL C
    .language_version:
      - 2
      - 0
    .max_flat_workgroup_size: 512
    .name:           _Z6mk_fwd4Args
    .private_segment_fixed_size: 0
    .sgpr_count:     108
    .sgpr_spill_count: 0
    .symbol:         _Z6mk_fwd4Args.kd
    .uniform_work_group_size: 1
    .uses_dynamic_stack: false
    .vgpr_count:     256
    .vgpr_spill_count: 0
    .wavefront_size: 64
